# attention: fewer VALU ops per tile (row-max chain without self-max canonicalisation, rescale amount computed only on the rare rescale path)
# baseline (speedup 1.0000x reference)
; #define SBAR() __builtin_amdgcn_sched_barrier(0)
; #define WBAR() do { asm volatile("s_waitcnt vmcnt(0) lgkmcnt(0)" ::: "memory"); __builtin_amdgcn_s_barrier(); asm volatile("" ::: "memory"); } while (0)
; template <bool FIRST>
; __device__ __forceinline__ void partialSM(f32x16& p0, f32x16& p1, f32x16& negm, float& dl, float& alpha) {
;     float pmax = p0[0];
; #pragma unroll
;     for (int r = 1; r < 16; ++r) pmax = fmaxf(pmax, p0[r]);
; #pragma unroll
;     for (int r = 0; r < 16; ++r) pmax = fmaxf(pmax, p1[r]);
;     { auto rr = __builtin_amdgcn_permlane32_swap(__float_as_uint(pmax), __float_as_uint(pmax), false, false);
;       pmax = fmaxf(__uint_as_float(rr[0]), __uint_as_float(rr[1])); }
; __device__ __forceinline__ void attn_unit(const unsigned char* __restrict__ Qb, const unsigned char* __restrict__ Kh, const unsigned char* __restrict__ VTh, f16* __restrict__ Ob, int seq, LAS char* lds) {
;     ...
;         SBAR(); qkt(pB0, pB1, KSL(j), ka0, ka1, qf, negm);
;         finishSM(pA0, pA1, pa); SBAR();
;         pv_d0(o, VSL(j - 1), va0, va1, pa); partialSM<false>(pB0, pB1, negm, dlB, alB);
;         WBAR();
;         { const int J = (j - 1) >> 1; if (J + 2 < NS) ISSUE(J + 2); }
.LBB0_589:
	s_bitcmp1_b32 s15, 0
	s_cselect_b32 s0, 0x6000, 0
	s_add_i32 s0, s0, 0
	v_add_u32_e32 v0, s0, v244
	v_add_u32_e32 v210, s0, v245
	v_add_u32_e32 v211, 0xf000, v0
	v_add_u32_e32 v212, 0xf000, v210
	ds_read_b128 v[2:5], v0 offset:61504
	ds_read_b128 v[6:9], v210 offset:61504
	v_exp_f32_e32 v14, v116
	v_exp_f32_e32 v15, v117
	v_exp_f32_e32 v12, v114
	v_exp_f32_e32 v13, v115
	s_waitcnt lgkmcnt(4)
	v_mfma_scale_f32_32x32x64_f8f6f4 v[144:159], v[202:209], v[184:191], v[96:111], v234, v233 op_sel_hi:[0,0,0]
	ds_read_b128 v[202:205], v211 offset:6208
	ds_read_b128 v[206:209], v212 offset:6208
	v_exp_f32_e32 v114, v118
	v_exp_f32_e32 v115, v119
	v_exp_f32_e32 v119, v120
	v_exp_f32_e32 v120, v121
	v_cvt_pk_fp8_f32 v117, v14, v15
	v_exp_f32_e32 v10, v112
	v_exp_f32_e32 v11, v113
	s_waitcnt lgkmcnt(4)
	v_mfma_scale_f32_32x32x64_f8f6f4 v[128:143], v[194:201], v[184:191], v[96:111], v234, v233 op_sel_hi:[0,0,0]
	ds_read_b128 v[194:197], v0 offset:61568
	ds_read_b128 v[198:201], v210 offset:61568
	v_exp_f32_e32 v121, v122
	v_exp_f32_e32 v122, v123
	v_exp_f32_e32 v123, v124
	v_exp_f32_e32 v124, v125
	v_cvt_pk_fp8_f32 v117, v114, v115 op_sel:[0,0,1]
	v_cvt_pk_fp8_f32 v118, v119, v120
	v_exp_f32_e32 v125, v126
	s_waitcnt lgkmcnt(4)
	v_mfma_scale_f32_32x32x64_f8f6f4 v[144:159], v[2:9], v[176:183], v[144:159], v234, v233 op_sel_hi:[0,0,0]
	ds_read_b128 v[2:5], v211 offset:6272
	ds_read_b128 v[6:9], v212 offset:6272
	v_exp_f32_e32 v126, v127
	v_cvt_pk_fp8_f32 v112, v228, v229
	v_cvt_pk_fp8_f32 v116, v10, v11
	v_cvt_pk_fp8_f32 v113, v226, v227
	v_cvt_pk_fp8_f32 v114, v222, v223
	v_cvt_pk_fp8_f32 v115, v166, v167
	s_waitcnt lgkmcnt(4)
	v_mfma_scale_f32_32x32x64_f8f6f4 v[128:143], v[202:209], v[176:183], v[128:143], v234, v233 op_sel_hi:[0,0,0]
	v_cvt_pk_fp8_f32 v119, v123, v124
	v_cvt_pk_fp8_f32 v112, v220, v221 op_sel:[0,0,1]
	v_cvt_pk_fp8_f32 v116, v12, v13 op_sel:[0,0,1]
	v_cvt_pk_fp8_f32 v113, v224, v225 op_sel:[0,0,1]
	v_cvt_pk_fp8_f32 v114, v162, v163 op_sel:[0,0,1]
	v_cvt_pk_fp8_f32 v118, v121, v122 op_sel:[0,0,1]
	s_waitcnt lgkmcnt(2)
	v_mfma_scale_f32_32x32x64_f8f6f4 v[144:159], v[194:201], v[168:175], v[144:159], v234, v233 op_sel_hi:[0,0,0]
	v_cvt_pk_fp8_f32 v115, v164, v165 op_sel:[0,0,1]
	v_cvt_pk_fp8_f32 v119, v125, v126 op_sel:[0,0,1]
	v_mov_b32_e32 v161, v160
	v_mov_b32_e32 v162, v160
	v_mov_b32_e32 v163, v160
	s_waitcnt lgkmcnt(0)
	v_mfma_scale_f32_32x32x64_f8f6f4 v[128:143], v[2:9], v[168:175], v[128:143], v234, v233 op_sel_hi:[0,0,0]
	v_mov_b32_e32 v164, v160
	v_mov_b32_e32 v165, v160
	v_mov_b32_e32 v166, v160
	v_mov_b32_e32 v167, v160
	s_add_i32 s66, s21, -2
	s_ashr_i32 s38, s66, 1
	s_mul_hi_i32 s0, s38, 0x55555556
	s_lshr_b32 s1, s0, 31
	s_add_i32 s0, s0, s1
	s_mul_i32 s0, s0, 3
	s_sub_i32 s0, s38, s0
	s_lshl_b32 s0, s0, 14
	s_add_i32 s0, s0, 0
	v_add_u32_e32 v0, s0, v241
	v_add_u32_e32 v11, s0, v240
	ds_read_b128 v[208:211], v0
	ds_read_b128 v[212:215], v11
	ds_read_b128 v[200:203], v0 offset:2048
	ds_read_b128 v[204:207], v11 offset:2048
	ds_read_b128 v[192:195], v0 offset:4096
	ds_read_b128 v[196:199], v11 offset:4096
	ds_read_b128 v[2:5], v0 offset:6144
	ds_read_b128 v[6:9], v11 offset:6144
	v_mov_b32_e32 v125, 0x19000
	v_lshl_add_u32 v126, v216, 4, v125
	v_lshl_add_u32 v127, v216, 2, v125
	ds_read_b128 v[120:123], v126
	ds_read_b32 v124, v127 offset:8192
	v_max_f32_e32 v0, v144, v145
	v_max3_f32 v0, v0, v146, v147
	v_max3_f32 v0, v0, v148, v149
	v_max3_f32 v0, v0, v150, v151
	v_max3_f32 v0, v0, v152, v153
	v_max3_f32 v0, v0, v154, v155
	v_max3_f32 v0, v0, v156, v157
	v_max3_f32 v0, v0, v158, v159
	s_waitcnt lgkmcnt(8)
	v_mfma_scale_f32_32x32x64_f8f6f4 v[64:79], v[112:119], v[208:215], v[64:79], v234, v234 op_sel_hi:[0,0,0]
	v_exp_f32_e32 v14, v144
	v_exp_f32_e32 v15, v145
	v_exp_f32_e32 v10, v148
	v_exp_f32_e32 v11, v149
	v_max3_f32 v0, v0, v128, v129
	v_max3_f32 v0, v0, v130, v131
	v_max3_f32 v0, v0, v132, v133
	v_max3_f32 v0, v0, v134, v135
	s_waitcnt lgkmcnt(6)
	v_mfma_scale_f32_32x32x64_f8f6f4 v[48:63], v[112:119], v[200:207], v[48:63], v234, v234 op_sel_hi:[0,0,0]
	v_exp_f32_e32 v12, v150
	v_exp_f32_e32 v13, v151
	v_max3_f32 v0, v0, v136, v137
	v_max3_f32 v0, v0, v138, v139
	v_max3_f32 v0, v0, v140, v141
	v_max3_f32 v0, v0, v142, v143
	s_waitcnt lgkmcnt(4)
	v_mfma_scale_f32_32x32x64_f8f6f4 v[32:47], v[112:119], v[192:199], v[32:47], v234, v234 op_sel_hi:[0,0,0]
	v_exp_f32_e32 v192, v146
	v_exp_f32_e32 v193, v147
	v_mov_b32_e32 v125, v0
	s_nop 1
	v_permlane32_swap_b32_e32 v0, v125
	s_waitcnt lgkmcnt(2)
	v_mfma_scale_f32_32x32x64_f8f6f4 v[16:31], v[112:119], v[2:9], v[16:31], v234, v234 op_sel_hi:[0,0,0]
	v_exp_f32_e32 v6, v152
	v_exp_f32_e32 v7, v153
	v_exp_f32_e32 v8, v154
	v_exp_f32_e32 v9, v155
	v_exp_f32_e32 v2, v156
	v_exp_f32_e32 v3, v157
	v_exp_f32_e32 v4, v158
	v_exp_f32_e32 v5, v159
	v_mfma_scale_f32_32x32x64_f8f6f4 v[80:95], v[112:119], v[160:167], v[80:95], v234, v234 op_sel_hi:[0,0,0]
	s_waitcnt vmcnt(0) lgkmcnt(0)
	s_barrier
	v_max_f32_e32 v0, v0, v125
	s_add_i32 s42, s38, 2
	v_cmp_ge_f32_e64 s[0:1], s67, v0
	s_cmp_ge_i32 s42, s14
	s_cbranch_scc1 .Lattn_noissue
	s_bitcmp1_b32 s21, 1
	s_cselect_b32 s44, 0x6000, 0
	v_add_u32_e32 v126, s44, v244
	v_add_u32_e32 v127, s44, v245
	ds_read_b128 v[208:211], v126 offset:49152
	ds_read_b128 v[212:215], v127 offset:49152
	s_ashr_i32 s43, s42, 31
	s_mul_i32 s38, s42, 0x18000
	s_mul_hi_i32 s39, s42, 0x18000
	s_add_u32 s38, s24, s38
	s_addc_u32 s39, s25, s39
	s_lshl_b64 s[40:41], s[42:43], 14
	s_add_u32 s40, s52, s40
	s_addc_u32 s41, s53, s41
	s_mul_hi_i32 s43, s42, 0x55555556
	s_lshr_b32 s67, s43, 31
	s_add_i32 s43, s43, s67
	s_mul_i32 s43, s43, 3
	s_sub_i32 s42, s42, s43
	s_lshl_b32 s67, s42, 14
	s_bitcmp1_b32 s66, 1
	s_mov_b32 s42, 0xa000
	s_cselect_b32 s66, 0x10000, s42
	s_add_i32 s42, s67, s28
	s_add_i32 s43, s29, s66
	s_and_b64 vcc, s[54:55], exec
	s_cselect_b32 s42, s42, s43
	s_mov_b32 m0, s42
	s_and_b64 vcc, exec, s[56:57]
	s_cselect_b32 s44, s38, s40
	s_cselect_b32 s45, s39, s41
	global_load_lds_dwordx4 v120, s[44:45]
	s_add_i32 s42, s67, s35
	s_add_i32 s43, s2, s66
	s_and_b64 vcc, s[58:59], exec
	s_cselect_b32 s42, s42, s43
	s_mov_b32 m0, s42
	s_and_b64 vcc, exec, s[4:5]
	s_cselect_b32 s44, s40, s38
	s_cselect_b32 s45, s41, s39
	global_load_lds_dwordx4 v121, s[44:45]
	s_add_i32 s42, s67, s26
	s_add_i32 s43, s27, s66
	s_and_b64 vcc, s[60:61], exec
	s_cselect_b32 s42, s42, s43
	s_mov_b32 m0, s42
	s_and_b64 vcc, exec, s[6:7]
	s_cselect_b32 s44, s40, s38
	s_cselect_b32 s45, s41, s39
	global_load_lds_dwordx4 v122, s[44:45]
	s_add_i32 s42, s67, s31
	s_add_i32 s43, s49, s66
	s_and_b64 vcc, s[62:63], exec
	s_cselect_b32 s42, s42, s43
	s_mov_b32 m0, s42
	s_and_b64 vcc, exec, s[8:9]
	s_cselect_b32 s44, s40, s38
	s_cselect_b32 s45, s41, s39
	global_load_lds_dwordx4 v123, s[44:45]
	s_add_i32 s42, s67, s18
	s_add_i32 s43, s33, s66
	s_and_b64 vcc, s[64:65], exec
	s_cselect_b32 s42, s42, s43
	s_mov_b32 m0, s42
	s_and_b64 vcc, exec, s[10:11]
	s_cselect_b32 s44, s40, s38
	s_cselect_b32 s45, s41, s39
	global_load_lds_dwordx4 v124, s[44:45]
	s_mov_b32 s67, 0x41000000
	ds_read_b128 v[120:123], v126 offset:55296
	ds_read_b128 v[124:127], v127 offset:55296
	s_cmp_lg_u64 s[0:1], exec
	s_cbranch_scc0 .LBB0_615
	s_branch .Lattn_fix1
.Lattn_noissue:
	s_bitcmp1_b32 s21, 1
	s_cselect_b32 s44, 0x6000, 0
	v_add_u32_e32 v126, s44, v244
	v_add_u32_e32 v127, s44, v245
	ds_read_b128 v[208:211], v126 offset:49152
	ds_read_b128 v[212:215], v127 offset:49152
	ds_read_b128 v[120:123], v126 offset:55296
	ds_read_b128 v[124:127], v127 offset:55296
	s_cmp_lg_u64 s[0:1], exec
	s_cbranch_scc0 .LBB0_615
.Lattn_fix1:
	v_add_f32_e32 v0, -4.0, v0
	v_max_f32_e32 v0, 0, v0
	v_exp_f32_e64 v112, -v0
	s_and_saveexec_b64 s[0:1], s[12:13]
	ds_write_b32 v243, v112 offset:128
	s_or_b64 exec, exec, s[0:1]
	s_waitcnt lgkmcnt(0)
	v_add_u32_e32 v113, s20, v242
	ds_read_b128 v[114:117], v113 offset:224
	ds_read_b128 v[118:121], v113 offset:192
	ds_read_b128 v[122:125], v113 offset:160
	ds_read_b128 v[144:147], v113 offset:128
	v_pk_add_f32 v[128:129], v[128:129], v[0:1] op_sel_hi:[1,0] neg_lo:[0,1] neg_hi:[0,1]
	s_waitcnt lgkmcnt(0)
	v_pk_mul_f32 v[76:77], v[76:77], v[114:115]
	v_pk_mul_f32 v[72:73], v[72:73], v[118:119]
	v_pk_mul_f32 v[68:69], v[68:69], v[122:123]
	v_pk_mul_f32 v[78:79], v[78:79], v[116:117]
	v_pk_mul_f32 v[74:75], v[74:75], v[120:121]
	v_pk_mul_f32 v[70:71], v[70:71], v[124:125]
	v_pk_mul_f32 v[66:67], v[66:67], v[146:147]
	v_pk_mul_f32 v[64:65], v[64:65], v[144:145]
	v_pk_mul_f32 v[60:61], v[60:61], v[114:115]
	v_pk_mul_f32 v[56:57], v[56:57], v[118:119]
	v_pk_mul_f32 v[52:53], v[52:53], v[122:123]
	v_pk_mul_f32 v[62:63], v[62:63], v[116:117]
	v_pk_mul_f32 v[58:59], v[58:59], v[120:121]
	v_pk_mul_f32 v[54:55], v[54:55], v[124:125]
	v_pk_mul_f32 v[50:51], v[50:51], v[146:147]
	v_pk_mul_f32 v[48:49], v[48:49], v[144:145]
	v_pk_mul_f32 v[44:45], v[44:45], v[114:115]
	v_pk_mul_f32 v[40:41], v[40:41], v[118:119]
	v_pk_mul_f32 v[36:37], v[36:37], v[122:123]
	v_pk_mul_f32 v[46:47], v[46:47], v[116:117]
	v_pk_mul_f32 v[42:43], v[42:43], v[120:121]
	v_pk_mul_f32 v[38:39], v[38:39], v[124:125]
	v_pk_mul_f32 v[34:35], v[34:35], v[146:147]
	v_pk_mul_f32 v[32:33], v[32:33], v[144:145]
	v_pk_mul_f32 v[28:29], v[28:29], v[114:115]
	v_pk_mul_f32 v[24:25], v[24:25], v[118:119]
	v_pk_mul_f32 v[20:21], v[20:21], v[122:123]
	v_pk_mul_f32 v[30:31], v[30:31], v[116:117]
	v_pk_mul_f32 v[26:27], v[26:27], v[120:121]
	v_pk_mul_f32 v[22:23], v[22:23], v[124:125]
	v_pk_mul_f32 v[18:19], v[18:19], v[146:147]
	v_pk_mul_f32 v[16:17], v[16:17], v[144:145]
	v_pk_mul_f32 v[92:93], v[92:93], v[114:115]
	v_pk_mul_f32 v[88:89], v[88:89], v[118:119]
	v_pk_mul_f32 v[84:85], v[84:85], v[122:123]
	v_pk_mul_f32 v[94:95], v[94:95], v[116:117]
	v_pk_mul_f32 v[90:91], v[90:91], v[120:121]
	v_pk_mul_f32 v[86:87], v[86:87], v[124:125]
	v_pk_mul_f32 v[82:83], v[82:83], v[146:147]
	v_pk_mul_f32 v[80:81], v[80:81], v[144:145]
	v_pk_add_f32 v[130:131], v[130:131], v[0:1] op_sel_hi:[1,0] neg_lo:[0,1] neg_hi:[0,1]
	v_pk_add_f32 v[132:133], v[132:133], v[0:1] op_sel_hi:[1,0] neg_lo:[0,1] neg_hi:[0,1]
	v_pk_add_f32 v[134:135], v[134:135], v[0:1] op_sel_hi:[1,0] neg_lo:[0,1] neg_hi:[0,1]
	v_pk_add_f32 v[136:137], v[136:137], v[0:1] op_sel_hi:[1,0] neg_lo:[0,1] neg_hi:[0,1]
	v_pk_add_f32 v[138:139], v[138:139], v[0:1] op_sel_hi:[1,0] neg_lo:[0,1] neg_hi:[0,1]
	v_pk_add_f32 v[140:141], v[140:141], v[0:1] op_sel_hi:[1,0] neg_lo:[0,1] neg_hi:[0,1]
	v_pk_mul_f32 v[4:5], v[4:5], v[112:113] op_sel_hi:[1,0]
	v_pk_mul_f32 v[2:3], v[2:3], v[112:113] op_sel_hi:[1,0]
	v_pk_mul_f32 v[8:9], v[8:9], v[112:113] op_sel_hi:[1,0]
	v_pk_mul_f32 v[6:7], v[6:7], v[112:113] op_sel_hi:[1,0]
	v_pk_mul_f32 v[12:13], v[12:13], v[112:113] op_sel_hi:[1,0]
	v_pk_mul_f32 v[10:11], v[10:11], v[112:113] op_sel_hi:[1,0]
	v_pk_mul_f32 v[192:193], v[192:193], v[112:113] op_sel_hi:[1,0]
	v_pk_mul_f32 v[14:15], v[14:15], v[112:113] op_sel_hi:[1,0]
	v_pk_add_f32 v[142:143], v[142:143], v[0:1] op_sel_hi:[1,0] neg_lo:[0,1] neg_hi:[0,1]
	v_sub_f32_e32 v111, v111, v0
	v_sub_f32_e32 v110, v110, v0
	v_sub_f32_e32 v109, v109, v0
	v_sub_f32_e32 v108, v108, v0
	v_sub_f32_e32 v107, v107, v0
	v_sub_f32_e32 v106, v106, v0
	v_sub_f32_e32 v105, v105, v0
	v_sub_f32_e32 v104, v104, v0
	v_sub_f32_e32 v103, v103, v0
	v_sub_f32_e32 v102, v102, v0
	v_sub_f32_e32 v101, v101, v0
	v_sub_f32_e32 v100, v100, v0
	v_sub_f32_e32 v99, v99, v0
	v_sub_f32_e32 v98, v98, v0
	v_sub_f32_e32 v97, v97, v0
	v_sub_f32_e32 v96, v96, v0
	s_bitcmp1_b32 s21, 1
	s_cselect_b32 s0, 0x6000, 0
	v_add_u32_e32 v126, s0, v244
	v_add_u32_e32 v127, s0, v245
	ds_read_b128 v[120:123], v126 offset:55296
	ds_read_b128 v[124:127], v127 offset:55296
; #define SBAR() __builtin_amdgcn_sched_barrier(0)
; #define FIX(a, dlt, P0, P1) do { if (__any((dlt) > 0.f)) { if (hi == 0) al_l[r32] = (a); asm volatile("s_waitcnt lgkmcnt(0)" ::: "memory"); \
;     _Pragma("unroll") for (int d = 0; d < 5; ++d) _Pragma("unroll") for (int r = 0; r < 16; ++r) o[d][r] *= al_l[crow(r, hi)]; \
;     _Pragma("unroll") for (int r = 0; r < 16; ++r) { P0[r] *= (a); P1[r] -= (dlt); negm[r] -= (dlt); } } } while (0)
; template <bool FIRST>
; __device__ __forceinline__ void partialSM(f32x16& p0, f32x16& p1, f32x16& negm, float& dl, float& alpha) {
;     float pmax = p0[0];
; #pragma unroll
;     for (int r = 1; r < 16; ++r) pmax = fmaxf(pmax, p0[r]);
; #pragma unroll
;     for (int r = 0; r < 16; ++r) pmax = fmaxf(pmax, p1[r]);
;     { auto rr = __builtin_amdgcn_permlane32_swap(__float_as_uint(pmax), __float_as_uint(pmax), false, false);
;       pmax = fmaxf(__uint_as_float(rr[0]), __uint_as_float(rr[1])); }
;     if (FIRST) {
;         dl = 0.f; alpha = 1.f; const float d0_ = pmax - SH;
; #pragma unroll
;         for (int r = 0; r < 16; ++r) { p0[r] -= d0_; p1[r] -= d0_; negm[r] -= d0_; }
;     } else {
;         const bool keep = __all(pmax <= SH + THRL);
;         dl = keep ? 0.f : fmaxf(pmax - SH, 0.f); alpha = __builtin_amdgcn_exp2f(-dl);
; __device__ __forceinline__ void attn_unit(const unsigned char* __restrict__ Qb, const unsigned char* __restrict__ Kh, const unsigned char* __restrict__ VTh, f16* __restrict__ Ob, int seq, LAS char* lds) {
;     ...
;         SBAR(); qkt(pA0, pA1, KSL(j + 1), ka0, ka1, qf, negm);
;         finishSM(pB0, pB1, pa); SBAR();
;         pv_d0(o, VSL(j), va0, va1, pa); partialSM<false>(pA0, pA1, negm, dlA, alA);
;         FIX(alA, dlA, pA0, pA1);
.LBB0_615:
	s_mul_hi_u32 s0, s15, 0xaaaaaaab
	s_lshr_b32 s0, s0, 1
	s_mul_i32 s0, s0, 0xffff4000
	s_bfe_i32 s1, s21, 0x10001
	s_and_b32 s1, s1, 0x6000
	s_add_i32 s1, s1, 0
	v_add_u32_e32 v0, s1, v244
	v_add_u32_e32 v161, s1, v245
	ds_read_b128 v[194:197], v0 offset:55360
	ds_read_b128 v[198:201], v161 offset:55360
	v_exp_f32_e32 v129, v129
	v_exp_f32_e32 v162, v133
	s_waitcnt lgkmcnt(4)
	v_mfma_scale_f32_32x32x64_f8f6f4 v[144:159], v[208:215], v[184:191], v[96:111], v234, v233 op_sel_hi:[0,0,0]
	ds_read_b128 v[202:205], v0 offset:49216
	ds_read_b128 v[206:209], v161 offset:49216
	v_exp_f32_e32 v130, v130
	v_exp_f32_e32 v131, v131
	v_exp_f32_e32 v134, v134
	v_exp_f32_e32 v135, v135
	v_exp_f32_e32 v136, v136
	v_exp_f32_e32 v137, v137
	v_exp_f32_e32 v140, v140
	v_exp_f32_e32 v141, v141
	v_exp_f32_e32 v138, v138
	v_exp_f32_e32 v139, v139
	v_exp_f32_e32 v142, v142
	v_exp_f32_e32 v143, v143
	s_waitcnt lgkmcnt(4)
	v_mfma_scale_f32_32x32x64_f8f6f4 v[112:127], v[120:127], v[184:191], v[96:111], v234, v233 op_sel_hi:[0,0,0]
	s_waitcnt lgkmcnt(2)
	v_mfma_scale_f32_32x32x64_f8f6f4 v[112:127], v[194:201], v[176:183], v[112:127], v234, v233 op_sel_hi:[0,0,0]
	s_waitcnt lgkmcnt(0)
	v_mfma_scale_f32_32x32x64_f8f6f4 v[144:159], v[202:209], v[176:183], v[144:159], v234, v233 op_sel_hi:[0,0,0]
	ds_read_b128 v[194:197], v0 offset:55424
	ds_read_b128 v[198:201], v161 offset:55424
	ds_read_b128 v[202:205], v0 offset:49280
	ds_read_b128 v[206:209], v161 offset:49280
	v_exp_f32_e32 v0, v128
	v_exp_f32_e32 v161, v132
	v_cvt_pk_fp8_f32 v132, v0, v129
	v_cvt_pk_fp8_f32 v133, v161, v162
	v_cvt_pk_fp8_f32 v128, v14, v15
	v_cvt_pk_fp8_f32 v132, v130, v131 op_sel:[0,0,1]
	v_cvt_pk_fp8_f32 v133, v134, v135 op_sel:[0,0,1]
	s_waitcnt lgkmcnt(0)
	v_mfma_scale_f32_32x32x64_f8f6f4 v[112:127], v[194:201], v[168:175], v[112:127], v234, v233 op_sel_hi:[0,0,0]
	v_cvt_pk_fp8_f32 v129, v10, v11
	v_cvt_pk_fp8_f32 v130, v6, v7
	v_cvt_pk_fp8_f32 v134, v136, v137
	v_cvt_pk_fp8_f32 v131, v2, v3
	v_cvt_pk_fp8_f32 v135, v140, v141
	v_cvt_pk_fp8_f32 v128, v192, v193 op_sel:[0,0,1]
	v_cvt_pk_fp8_f32 v129, v12, v13 op_sel:[0,0,1]
	v_cvt_pk_fp8_f32 v130, v8, v9 op_sel:[0,0,1]
	v_cvt_pk_fp8_f32 v134, v138, v139 op_sel:[0,0,1]
	v_cvt_pk_fp8_f32 v131, v4, v5 op_sel:[0,0,1]
	v_cvt_pk_fp8_f32 v135, v142, v143 op_sel:[0,0,1]
	v_or_b32_e32 v10, s0, v218
	v_or_b32_e32 v11, s0, v250
	v_add_u32_e32 v10, v247, v10
	v_add_u32_e32 v11, v247, v11
	ds_read_b128 v[2:5], v10
	ds_read_b128 v[6:9], v11
	v_mfma_scale_f32_32x32x64_f8f6f4 v[144:159], v[202:209], v[168:175], v[144:159], v234, v233 op_sel_hi:[0,0,0]
	ds_read_b128 v[194:197], v10 offset:2048
	ds_read_b128 v[198:201], v11 offset:2048
	v_mov_b32_e32 v161, v160
	v_mov_b32_e32 v162, v160
	v_mov_b32_e32 v163, v160
	v_mov_b32_e32 v164, v160
	v_mov_b32_e32 v165, v160
	v_mov_b32_e32 v166, v160
	v_mov_b32_e32 v167, v160
	s_waitcnt lgkmcnt(2)
	v_mfma_scale_f32_32x32x64_f8f6f4 v[64:79], v[128:135], v[2:9], v[64:79], v234, v234 op_sel_hi:[0,0,0]
	ds_read_b128 v[2:5], v10 offset:4096
	ds_read_b128 v[6:9], v11 offset:4096
	s_waitcnt lgkmcnt(2)
	v_mfma_scale_f32_32x32x64_f8f6f4 v[48:63], v[128:135], v[194:201], v[48:63], v234, v234 op_sel_hi:[0,0,0]
	ds_read_b128 v[194:197], v10 offset:6144
	ds_read_b128 v[198:201], v11 offset:6144
	s_nop 2
	v_exp_f32_e32 v228, v144
	v_exp_f32_e32 v229, v145
	v_exp_f32_e32 v220, v146
	v_exp_f32_e32 v221, v147
	v_exp_f32_e32 v226, v148
	v_exp_f32_e32 v227, v149
	v_exp_f32_e32 v224, v150
	v_exp_f32_e32 v225, v151
	v_exp_f32_e32 v222, v152
	v_exp_f32_e32 v223, v153
	v_max_f32_e32 v0, v144, v145
	s_waitcnt lgkmcnt(2)
	v_mfma_scale_f32_32x32x64_f8f6f4 v[32:47], v[128:135], v[2:9], v[32:47], v234, v234 op_sel_hi:[0,0,0]
	v_max3_f32 v0, v0, v146, v147
	v_max3_f32 v0, v0, v148, v149
	v_max3_f32 v0, v0, v150, v151
	v_max3_f32 v0, v0, v152, v153
	v_max3_f32 v0, v0, v154, v155
	v_max3_f32 v0, v0, v156, v157
	v_max3_f32 v0, v0, v158, v159
	s_waitcnt lgkmcnt(0)
	v_mfma_scale_f32_32x32x64_f8f6f4 v[16:31], v[128:135], v[194:201], v[16:31], v234, v234 op_sel_hi:[0,0,0]
	s_bitcmp0_b32 s15, 0
	s_cselect_b32 s1, 0x6000, 0
	v_add_u32_e32 v12, s1, v244
	v_add_u32_e32 v13, s1, v245
	v_add_u32_e32 v14, 0xf000, v12
	v_add_u32_e32 v15, 0xf000, v13
	ds_read_b128 v[202:205], v12 offset:61440
	ds_read_b128 v[206:209], v13 offset:61440
	ds_read_b128 v[194:197], v14 offset:6144
	ds_read_b128 v[198:201], v15 offset:6144
	v_max3_f32 v0, v0, v112, v113
	v_max3_f32 v0, v0, v114, v115
	v_max3_f32 v0, v0, v116, v117
	v_max3_f32 v0, v0, v118, v119
	v_max3_f32 v0, v0, v120, v121
	v_max3_f32 v0, v0, v122, v123
	v_mfma_scale_f32_32x32x64_f8f6f4 v[80:95], v[128:135], v[160:167], v[80:95], v234, v234 op_sel_hi:[0,0,0]
	v_max3_f32 v0, v0, v124, v125
	v_max3_f32 v0, v0, v126, v127
	v_mov_b32_e32 v2, v0
	s_nop 1
	v_permlane32_swap_b32_e32 v0, v2
	v_max_f32_e32 v0, v0, v2
	v_cmp_ge_f32_e32 vcc, s67, v0
	v_exp_f32_e32 v162, v154
	s_cmp_lg_u64 vcc, exec
	v_exp_f32_e32 v163, v155
	v_exp_f32_e32 v166, v156
	v_exp_f32_e32 v167, v157
	v_exp_f32_e32 v164, v158
	v_exp_f32_e32 v165, v159
	s_cbranch_scc0 .LBB0_588
	v_add_f32_e32 v2, -4.0, v0
	v_max_f32_e32 v2, 0, v2
	v_exp_f32_e64 v0, -v2
	s_and_saveexec_b64 s[0:1], s[12:13]
	s_cbranch_execz .LBB0_587
	ds_write_b32 v243, v0 offset:128
	s_branch .LBB0_587
